# modulate shift/scale ladder de-serialised in two inlined copies (layer-0 group loop and layer-1 out-projection phase): 14 loads hoisted next to the row loads, single wait
# speedup vs baseline: 1.0057x; 1.0057x over previous
;   DI const float* x() const { return (const float*)sp[0]; }
;   DI const float* ctx() const { return (const float*)sp[2]; }
;   DI const float* ln_g() const { return (const float*)sp[6]; }
;   DI const float* ln_b() const { return (const float*)sp[7]; }
; DI float wsum(float v) { for (int o = 32; o > 0; o >>= 1) v += __shfl_xor(v, o); return v; }
; DI void row_ln(float (&v)[32], const float* __restrict__ g, const float* __restrict__ bta, int lane) {
;   float sm = 0.f;
; #pragma unroll
;   for (int i = 0; i < 32; ++i) sm += v[i];
;   const float mean = wsum(sm) * (1.f / DM);
;   float sq = 0.f;
; #pragma unroll
;   for (int i = 0; i < 32; ++i) { v[i] -= mean; sq += v[i] * v[i]; }
; DI void phase_mod(const Params& p, int g, int layer, char* smem) {
;     ...
;   for (int i = blockIdx.x * 4 + w; i < MG; i += gridDim.x * 4) {
;     const long r = (long)g * MG + i; const int b = (int)(r / T), t = (int)(r % T);
;     float v[32];
;     if (layer == 0) {
;       const float* s = t < CTX ? p.ctx() + ((long)b * CTX + t) * DM : p.x() + ((long)b * SEQ + (t - CTX)) * DM;
; #pragma unroll
;       for (int j = 0; j < 8; ++j) { const f32x4 a = *(const f32x4*)(s + lane * 4 + 256 * j); v[4 * j] = a[0]; v[4 * j + 1] = a[1]; v[4 * j + 2] = a[2]; v[4 * j + 3] = a[3]; }
;     } else {
;       float* s = P_ZX + r * DM;
; #pragma unroll
;       for (int j = 0; j < 8; ++j) { const f32x4 a = *(const f32x4*)(s + lane * 4 + 256 * j); v[4 * j] = a[0]; v[4 * j + 1] = a[1]; v[4 * j + 2] = a[2]; v[4 * j + 3] = a[3]; }
;       row_ln(v, p.ln_g(), p.ln_b(), lane);
.LBB0_2215:
	v_ashrrev_i32_e32 v81, 31, v80
	v_lshl_add_u64 v[0:1], v[80:81], 0, s[42:43]
	v_mul_hi_u32 v184, v0, s61
	v_mad_u64_u32 v[2:3], s[4:5], v1, s61, v[184:185]
	v_mov_b32_e32 v184, v3
	v_mov_b32_e32 v3, v185
	v_mad_u64_u32 v[2:3], s[4:5], v0, s44, v[2:3]
	v_mov_b32_e32 v2, v3
	v_mov_b32_e32 v3, v185
	v_lshl_add_u64 v[2:3], v[184:185], 0, v[2:3]
	v_mad_u64_u32 v[2:3], s[4:5], v1, s44, v[2:3]
	v_ashrrev_i32_e32 v4, 31, v1
	v_mad_u64_u32 v[2:3], s[4:5], v4, s61, v[2:3]
	v_mul_lo_u32 v5, v4, s44
	v_mul_lo_u32 v4, v4, s61
	v_add3_u32 v3, v4, v3, v5
	v_ashrrev_i64 v[4:5], 7, v[2:3]
	v_lshrrev_b32_e32 v184, 31, v3
	v_lshl_add_u64 v[88:89], v[4:5], 0, v[184:185]
	v_mad_u64_u32 v[2:3], s[4:5], v88, s52, 0
	v_mov_b32_e32 v4, v3
	v_mad_u64_u32 v[4:5], s[4:5], v89, s52, v[4:5]
	v_sub_co_u32_e32 v90, vcc, v0, v2
	v_mov_b32_e32 v12, 0x12230
	s_nop 0
	v_subb_co_u32_e32 v91, vcc, v1, v4, vcc
	v_lshlrev_b64 v[0:1], 13, v[0:1]
	v_lshl_add_u64 v[94:95], v[84:85], 0, v[0:1]
	global_load_dwordx4 v[20:23], v[94:95], off
	global_load_dwordx4 v[32:35], v[94:95], off offset:1024
	global_load_dwordx4 v[40:43], v[94:95], off offset:2048
	global_load_dwordx4 v[48:51], v[94:95], off offset:3072
	v_add_co_u32_e32 v92, vcc, s9, v94
	v_mov_b32_e32 v87, v185
	s_nop 0
	v_addc_co_u32_e32 v93, vcc, 0, v95, vcc
	global_load_dwordx4 v[24:27], v[92:93], off
	global_load_dwordx4 v[8:11], v[92:93], off offset:1024
	global_load_dwordx4 v[4:7], v[92:93], off offset:2048
	global_load_dwordx4 v[0:3], v[92:93], off offset:3072
	ds_read_b128 v[12:15], v12
	s_waitcnt lgkmcnt(0)
	v_lshl_add_u64 v[54:55], v[12:13], 0, v[86:87]
	v_add_co_u32_e32 v140, vcc, s9, v54
	v_lshl_add_u64 v[52:53], v[14:15], 0, v[86:87]
	s_nop 0
	v_addc_co_u32_e32 v141, vcc, 0, v55, vcc
	v_add_co_u32_e32 v142, vcc, s9, v52
	s_waitcnt vmcnt(0)
	v_add_f32_e32 v16, 0, v20
	v_add_f32_e32 v16, v21, v16
	v_add_f32_e32 v16, v22, v16
	v_add_f32_e32 v16, v23, v16
	v_add_f32_e32 v16, v32, v16
	v_add_f32_e32 v16, v33, v16
	v_add_f32_e32 v16, v34, v16
	v_add_f32_e32 v16, v35, v16
	v_add_f32_e32 v16, v40, v16
	v_add_f32_e32 v16, v41, v16
	v_add_f32_e32 v16, v42, v16
	v_add_f32_e32 v16, v43, v16
	v_add_f32_e32 v16, v48, v16
	v_add_f32_e32 v16, v49, v16
	v_add_f32_e32 v16, v50, v16
	v_add_f32_e32 v16, v51, v16
	v_add_f32_e32 v16, v24, v16
	v_add_f32_e32 v16, v25, v16
	v_add_f32_e32 v16, v26, v16
	v_add_f32_e32 v16, v27, v16
	v_add_f32_e32 v16, v8, v16
	v_add_f32_e32 v16, v9, v16
	v_add_f32_e32 v16, v10, v16
	v_add_f32_e32 v16, v11, v16
	v_add_f32_e32 v16, v4, v16
	v_add_f32_e32 v16, v5, v16
	v_add_f32_e32 v16, v6, v16
	v_add_f32_e32 v16, v7, v16
	v_add_f32_e32 v16, v0, v16
	v_add_f32_e32 v16, v1, v16
	v_add_f32_e32 v16, v2, v16
	v_add_f32_e32 v16, v3, v16
	ds_bpermute_b32 v17, v134, v16
	v_addc_co_u32_e32 v143, vcc, 0, v53, vcc
	s_waitcnt lgkmcnt(0)
	v_add_f32_e32 v16, v16, v17
	ds_bpermute_b32 v17, v135, v16
	s_waitcnt lgkmcnt(0)
	v_add_f32_e32 v16, v16, v17
	ds_bpermute_b32 v17, v136, v16
	s_waitcnt lgkmcnt(0)
	v_add_f32_e32 v16, v16, v17
	ds_bpermute_b32 v17, v137, v16
	s_waitcnt lgkmcnt(0)
	v_add_f32_e32 v16, v16, v17
	ds_bpermute_b32 v17, v138, v16
	s_waitcnt lgkmcnt(0)
	v_add_f32_e32 v16, v16, v17
	ds_bpermute_b32 v17, v139, v16
	s_waitcnt lgkmcnt(0)
	v_add_f32_e32 v16, v16, v17
	v_mul_f32_e32 v72, 0x3a000000, v16
	global_load_dwordx4 v[12:15], v[54:55], off
	global_load_dwordx4 v[16:19], v[52:53], off
	v_pk_add_f32 v[76:77], v[20:21], v[72:73] op_sel_hi:[1,0] neg_lo:[0,1] neg_hi:[0,1]
	v_pk_add_f32 v[74:75], v[22:23], v[72:73] op_sel_hi:[1,0] neg_lo:[0,1] neg_hi:[0,1]
	v_pk_mul_f32 v[78:79], v[76:77], v[76:77]
	global_load_dwordx4 v[20:23], v[54:55], off offset:1024
	global_load_dwordx4 v[28:31], v[52:53], off offset:1024
	v_pk_mul_f32 v[112:113], v[74:75], v[74:75]
	v_pk_add_f32 v[98:99], v[32:33], v[72:73] op_sel_hi:[1,0] neg_lo:[0,1] neg_hi:[0,1]
	v_pk_add_f32 v[96:97], v[34:35], v[72:73] op_sel_hi:[1,0] neg_lo:[0,1] neg_hi:[0,1]
	global_load_dwordx4 v[32:35], v[54:55], off offset:2048
	global_load_dwordx4 v[36:39], v[52:53], off offset:2048
	v_pk_add_f32 v[102:103], v[40:41], v[72:73] op_sel_hi:[1,0] neg_lo:[0,1] neg_hi:[0,1]
	v_pk_add_f32 v[100:101], v[42:43], v[72:73] op_sel_hi:[1,0] neg_lo:[0,1] neg_hi:[0,1]
	global_load_dwordx4 v[40:43], v[54:55], off offset:3072
	global_load_dwordx4 v[44:47], v[52:53], off offset:3072
	v_pk_add_f32 v[106:107], v[48:49], v[72:73] op_sel_hi:[1,0] neg_lo:[0,1] neg_hi:[0,1]
	v_pk_add_f32 v[104:105], v[50:51], v[72:73] op_sel_hi:[1,0] neg_lo:[0,1] neg_hi:[0,1]
	global_load_dwordx4 v[48:51], v[140:141], off
	global_load_dwordx4 v[52:55], v[142:143], off
	v_pk_add_f32 v[110:111], v[24:25], v[72:73] op_sel_hi:[1,0] neg_lo:[0,1] neg_hi:[0,1]
	v_pk_add_f32 v[108:109], v[26:27], v[72:73] op_sel_hi:[1,0] neg_lo:[0,1] neg_hi:[0,1]
	global_load_dwordx4 v[56:59], v[140:141], off offset:1024
	global_load_dwordx4 v[60:63], v[142:143], off offset:1024
	v_pk_add_f32 v[116:117], v[8:9], v[72:73] op_sel_hi:[1,0] neg_lo:[0,1] neg_hi:[0,1]
	v_pk_add_f32 v[114:115], v[10:11], v[72:73] op_sel_hi:[1,0] neg_lo:[0,1] neg_hi:[0,1]
	global_load_dwordx4 v[64:67], v[140:141], off offset:2048
	global_load_dwordx4 v[68:71], v[142:143], off offset:2048
	global_load_dwordx4 v[8:11], v[140:141], off offset:3072
	global_load_dwordx4 v[24:27], v[142:143], off offset:3072
	v_add_f32_e32 v78, v78, v79
	v_add_f32_e32 v78, v112, v78
	v_pk_mul_f32 v[118:119], v[98:99], v[98:99]
	v_add_f32_e32 v78, v113, v78
	v_add_f32_e32 v78, v118, v78
	v_pk_mul_f32 v[120:121], v[96:97], v[96:97]
	v_add_f32_e32 v78, v119, v78
	v_add_f32_e32 v78, v120, v78
	v_pk_mul_f32 v[122:123], v[102:103], v[102:103]
	v_add_f32_e32 v78, v121, v78
; DI unsigned cvtpk(float lo, float hi) { f32x2_t v = {lo, hi}; bf16x2_t b = __builtin_convertvector(v, bf16x2_t); return __builtin_bit_cast(unsigned, b); }
; DI float wsum(float v) { for (int o = 32; o > 0; o >>= 1) v += __shfl_xor(v, o); return v; }
; DI void row_ln(float (&v)[32], const float* __restrict__ g, const float* __restrict__ bta, int lane) {
;     ...
;   for (int i = 0; i < 32; ++i) { v[i] -= mean; sq += v[i] * v[i]; }
;   const float rstd = rsqrtf(wsum(sq) * (1.f / DM) + EPS);
; #pragma unroll
;   for (int j = 0; j < 8; ++j) {
;     const f32x4 gg = *(const f32x4*)(g + lane * 4 + 256 * j), bb = *(const f32x4*)(bta + lane * 4 + 256 * j);
; #pragma unroll
;     for (int e = 0; e < 4; ++e) v[4 * j + e] = v[4 * j + e] * rstd * gg[e] + bb[e];
;   }
; DI void phase_mod(const Params& p, int g, int layer, char* smem) {
;     ...
;       for (int j = 0; j < 8; ++j) { const f32x4 o = {v[4 * j], v[4 * j + 1], v[4 * j + 2], v[4 * j + 3]}; *(f32x4*)(s + lane * 4 + 256 * j) = o; }
;     }
;     const float* md = P_MOD + ((long)layer * 9 + (t < CTX ? 8 : b)) * 6144;
; #pragma unroll
;     for (int j = 0; j < 8; ++j) {
;       const f32x4 sh = *(const f32x4*)(md + lane * 4 + 256 * j), sc = *(const f32x4*)(md + 2048 + lane * 4 + 256 * j);
;       u32x2 o = {cvtpk(v[4 * j] * (1.f + sc[0]) + sh[0], v[4 * j + 1] * (1.f + sc[1]) + sh[1]), cvtpk(v[4 * j + 2] * (1.f + sc[2]) + sh[2], v[4 * j + 3] * (1.f + sc[3]) + sh[3])};
;       *reinterpret_cast<u32x2*>(h + (long)i * DM + lane * 4 + 256 * j) = o;
	v_add_f32_e32 v78, v122, v78
	v_pk_mul_f32 v[124:125], v[100:101], v[100:101]
	v_add_f32_e32 v78, v123, v78
	v_add_f32_e32 v78, v124, v78
	v_pk_mul_f32 v[126:127], v[106:107], v[106:107]
	v_add_f32_e32 v78, v125, v78
	v_add_f32_e32 v78, v126, v78
	v_pk_mul_f32 v[128:129], v[104:105], v[104:105]
	v_add_f32_e32 v78, v127, v78
	v_add_f32_e32 v78, v128, v78
	v_pk_mul_f32 v[130:131], v[110:111], v[110:111]
	v_add_f32_e32 v78, v129, v78
	v_add_f32_e32 v78, v130, v78
	v_pk_mul_f32 v[132:133], v[108:109], v[108:109]
	v_add_f32_e32 v78, v131, v78
	v_add_f32_e32 v78, v132, v78
	v_pk_mul_f32 v[144:145], v[116:117], v[116:117]
	v_add_f32_e32 v78, v133, v78
	v_add_f32_e32 v78, v144, v78
	v_pk_mul_f32 v[146:147], v[114:115], v[114:115]
	v_add_f32_e32 v78, v145, v78
	v_pk_add_f32 v[4:5], v[4:5], v[72:73] op_sel_hi:[1,0] neg_lo:[0,1] neg_hi:[0,1]
	v_add_f32_e32 v78, v146, v78
	v_pk_mul_f32 v[148:149], v[4:5], v[4:5]
	v_add_f32_e32 v78, v147, v78
	v_pk_add_f32 v[6:7], v[6:7], v[72:73] op_sel_hi:[1,0] neg_lo:[0,1] neg_hi:[0,1]
	v_add_f32_e32 v78, v148, v78
	v_pk_mul_f32 v[150:151], v[6:7], v[6:7]
	v_add_f32_e32 v78, v149, v78
	v_pk_add_f32 v[0:1], v[0:1], v[72:73] op_sel_hi:[1,0] neg_lo:[0,1] neg_hi:[0,1]
	v_add_f32_e32 v78, v150, v78
	v_pk_mul_f32 v[140:141], v[0:1], v[0:1]
	v_add_f32_e32 v78, v151, v78
	v_pk_add_f32 v[2:3], v[2:3], v[72:73] op_sel_hi:[1,0] neg_lo:[0,1] neg_hi:[0,1]
	v_add_f32_e32 v78, v140, v78
	v_pk_mul_f32 v[72:73], v[2:3], v[2:3]
	v_add_f32_e32 v78, v141, v78
	v_add_f32_e32 v72, v72, v78
	v_add_f32_e32 v72, v73, v72
	ds_bpermute_b32 v73, v134, v72
	s_waitcnt lgkmcnt(0)
	v_add_f32_e32 v72, v72, v73
	ds_bpermute_b32 v73, v135, v72
	s_waitcnt lgkmcnt(0)
	v_add_f32_e32 v72, v72, v73
	ds_bpermute_b32 v73, v136, v72
	s_waitcnt lgkmcnt(0)
	v_add_f32_e32 v72, v72, v73
	ds_bpermute_b32 v73, v137, v72
	s_waitcnt lgkmcnt(0)
	v_add_f32_e32 v72, v72, v73
	ds_bpermute_b32 v73, v138, v72
	s_waitcnt lgkmcnt(0)
	v_add_f32_e32 v72, v72, v73
	ds_bpermute_b32 v73, v139, v72
	s_waitcnt lgkmcnt(0)
	v_add_f32_e32 v72, v72, v73
	v_fmamk_f32 v72, v72, 0x3a000000, v152
	v_cmp_gt_f32_e32 vcc, s12, v72
	v_mul_f32_e32 v73, 0x4b800000, v72
	s_nop 0
	v_cndmask_b32_e32 v72, v72, v73, vcc
	v_rsq_f32_e32 v72, v72
	s_nop 0
	v_mul_f32_e32 v73, 0x45800000, v72
	v_cndmask_b32_e32 v112, v72, v73, vcc
	v_pk_mul_f32 v[72:73], v[76:77], v[112:113] op_sel_hi:[1,0]
	v_pk_mul_f32 v[0:1], v[0:1], v[112:113] op_sel_hi:[1,0]
	s_waitcnt vmcnt(0)
	v_pk_fma_f32 v[76:77], v[12:13], v[72:73], v[16:17]
	v_pk_mul_f32 v[12:13], v[74:75], v[112:113] op_sel_hi:[1,0]
	v_pk_fma_f32 v[0:1], v[8:9], v[0:1], v[24:25]
	v_pk_fma_f32 v[78:79], v[14:15], v[12:13], v[18:19]
	v_pk_mul_f32 v[12:13], v[98:99], v[112:113] op_sel_hi:[1,0]
	v_pk_mul_f32 v[2:3], v[2:3], v[112:113] op_sel_hi:[1,0]
	v_pk_fma_f32 v[72:73], v[20:21], v[12:13], v[28:29]
	v_pk_mul_f32 v[12:13], v[96:97], v[112:113] op_sel_hi:[1,0]
	v_mad_u64_u32 v[8:9], s[4:5], v88, s45, v[186:187]
	v_pk_fma_f32 v[74:75], v[22:23], v[12:13], v[30:31]
	v_pk_mul_f32 v[12:13], v[102:103], v[112:113] op_sel_hi:[1,0]
	v_pk_fma_f32 v[2:3], v[10:11], v[2:3], v[26:27]
	v_pk_fma_f32 v[28:29], v[32:33], v[12:13], v[36:37]
	v_pk_mul_f32 v[12:13], v[100:101], v[112:113] op_sel_hi:[1,0]
	v_mov_b32_e32 v10, v9
	v_pk_fma_f32 v[30:31], v[34:35], v[12:13], v[38:39]
	v_pk_mul_f32 v[12:13], v[106:107], v[112:113] op_sel_hi:[1,0]
	v_mad_u64_u32 v[10:11], s[4:5], v89, s45, v[10:11]
	v_cmp_lt_i64_e32 vcc, s[82:83], v[90:91]
	v_pk_fma_f32 v[20:21], v[40:41], v[12:13], v[44:45]
	v_pk_mul_f32 v[12:13], v[104:105], v[112:113] op_sel_hi:[1,0]
	v_cndmask_b32_e32 v9, 0, v10, vcc
	v_cndmask_b32_e32 v8, v223, v8, vcc
	v_pk_fma_f32 v[22:23], v[42:43], v[12:13], v[46:47]
	v_pk_mul_f32 v[12:13], v[110:111], v[112:113] op_sel_hi:[1,0]
	v_lshl_add_u64 v[8:9], s[6:7], 0, v[8:9]
	v_pk_fma_f32 v[16:17], v[48:49], v[12:13], v[52:53]
	v_pk_mul_f32 v[12:13], v[108:109], v[112:113] op_sel_hi:[1,0]
	v_lshl_add_u64 v[36:37], v[8:9], 0, v[86:87]
	s_movk_i32 s4, 0x3000
	v_pk_fma_f32 v[18:19], v[50:51], v[12:13], v[54:55]
	v_pk_mul_f32 v[12:13], v[116:117], v[112:113] op_sel_hi:[1,0]
	v_pk_mul_f32 v[14:15], v[114:115], v[112:113] op_sel_hi:[1,0]
	v_pk_mul_f32 v[4:5], v[4:5], v[112:113] op_sel_hi:[1,0]
	v_pk_mul_f32 v[6:7], v[6:7], v[112:113] op_sel_hi:[1,0]
	v_add_co_u32_e32 v10, vcc, s4, v36
	v_pk_fma_f32 v[12:13], v[56:57], v[12:13], v[60:61]
	v_pk_fma_f32 v[14:15], v[58:59], v[14:15], v[62:63]
	v_pk_fma_f32 v[4:5], v[64:65], v[4:5], v[68:69]
	v_pk_fma_f32 v[6:7], v[66:67], v[6:7], v[70:71]
	global_store_dwordx4 v[94:95], v[76:79], off
	global_store_dwordx4 v[94:95], v[72:75], off offset:1024
	global_store_dwordx4 v[94:95], v[28:31], off offset:2048
	global_store_dwordx4 v[94:95], v[20:23], off offset:3072
	global_store_dwordx4 v[92:93], v[16:19], off
	global_store_dwordx4 v[92:93], v[12:15], off offset:1024
	global_store_dwordx4 v[92:93], v[4:7], off offset:2048
	global_store_dwordx4 v[92:93], v[0:3], off offset:3072
	v_addc_co_u32_e32 v11, vcc, 0, v37, vcc
	global_load_dwordx4 v[24:27], v[36:37], off
	global_load_dwordx4 v[32:35], v[10:11], off offset:-4096
	v_lshlrev_b64 v[8:9], 12, v[80:81]
	v_lshl_add_u64 v[8:9], v[82:83], 0, v[8:9]
	v_lshl_add_u64 v[38:39], v[36:37], 0, s[10:11]
	v_add_u32_e32 v80, s8, v80
	s_movk_i32 s4, 0x11ff
	global_load_dwordx4 v[176:179], v[36:37], off offset:1024
	global_load_dwordx4 v[180:183], v[38:39], off offset:1024
	global_load_dwordx4 v[188:191], v[36:37], off offset:2048
	global_load_dwordx4 v[192:195], v[38:39], off offset:2048
	global_load_dwordx4 v[216:219], v[36:37], off offset:3072
	global_load_dwordx4 v[224:227], v[38:39], off offset:3072
	global_load_dwordx4 v[228:231], v[38:39], off offset:-4096
	global_load_dwordx4 v[232:235], v[10:11], off
	global_load_dwordx4 v[236:239], v[38:39], off offset:-3072
	global_load_dwordx4 v[240:243], v[10:11], off offset:1024
	global_load_dwordx4 v[244:247], v[38:39], off offset:-2048
	global_load_dwordx4 v[248:251], v[10:11], off offset:2048
	global_load_dwordx4 v[210:213], v[38:39], off offset:-1024
	global_load_dwordx4 v[198:201], v[10:11], off offset:3072
	s_waitcnt vmcnt(0)
; DI unsigned cvtpk(float lo, float hi) { f32x2_t v = {lo, hi}; bf16x2_t b = __builtin_convertvector(v, bf16x2_t); return __builtin_bit_cast(unsigned, b); }
; DI void phase_mod(const Params& p, int g, int layer, char* smem) {
;     ...
;     const float* md = P_MOD + ((long)layer * 9 + (t < CTX ? 8 : b)) * 6144;
; #pragma unroll
;     for (int j = 0; j < 8; ++j) {
;       const f32x4 sh = *(const f32x4*)(md + lane * 4 + 256 * j), sc = *(const f32x4*)(md + 2048 + lane * 4 + 256 * j);
;       u32x2 o = {cvtpk(v[4 * j] * (1.f + sc[0]) + sh[0], v[4 * j + 1] * (1.f + sc[1]) + sh[1]), cvtpk(v[4 * j + 2] * (1.f + sc[2]) + sh[2], v[4 * j + 3] * (1.f + sc[3]) + sh[3])};
;       *reinterpret_cast<u32x2*>(h + (long)i * DM + lane * 4 + 256 * j) = o;
	v_pk_add_f32 v[32:33], v[32:33], 1.0 op_sel_hi:[1,0]
	s_nop 0
	v_pk_fma_f32 v[24:25], v[32:33], v[76:77], v[24:25]
	v_pk_add_f32 v[32:33], v[34:35], 1.0 op_sel_hi:[1,0]
	v_cvt_pk_bf16_f32 v24, v24, v25
	v_pk_fma_f32 v[26:27], v[32:33], v[78:79], v[26:27]
	s_nop 0
	v_cvt_pk_bf16_f32 v25, v26, v27
	global_store_dwordx2 v[8:9], v[24:25], off
	s_nop 0
	v_pk_add_f32 v[180:181], v[180:181], 1.0 op_sel_hi:[1,0]
	s_nop 0
	v_pk_fma_f32 v[176:177], v[180:181], v[72:73], v[176:177]
	v_pk_add_f32 v[180:181], v[182:183], 1.0 op_sel_hi:[1,0]
	v_cvt_pk_bf16_f32 v176, v176, v177
	v_pk_fma_f32 v[178:179], v[180:181], v[74:75], v[178:179]
	s_nop 0
	v_cvt_pk_bf16_f32 v177, v178, v179
	global_store_dwordx2 v[8:9], v[176:177], off offset:512
	s_nop 0
	v_pk_add_f32 v[192:193], v[192:193], 1.0 op_sel_hi:[1,0]
	s_nop 0
	v_pk_fma_f32 v[188:189], v[192:193], v[28:29], v[188:189]
	v_pk_add_f32 v[28:29], v[194:195], 1.0 op_sel_hi:[1,0]
	v_cvt_pk_bf16_f32 v188, v188, v189
	v_pk_fma_f32 v[190:191], v[28:29], v[30:31], v[190:191]
	s_nop 0
	v_cvt_pk_bf16_f32 v189, v190, v191
	global_store_dwordx2 v[8:9], v[188:189], off offset:1024
	s_nop 0
	v_pk_add_f32 v[224:225], v[224:225], 1.0 op_sel_hi:[1,0]
	s_nop 0
	v_pk_fma_f32 v[20:21], v[224:225], v[20:21], v[216:217]
	v_pk_add_f32 v[216:217], v[226:227], 1.0 op_sel_hi:[1,0]
	v_cvt_pk_bf16_f32 v20, v20, v21
	v_pk_fma_f32 v[22:23], v[216:217], v[22:23], v[218:219]
	v_add_co_u32_e32 v224, vcc, s9, v36
	v_cvt_pk_bf16_f32 v21, v22, v23
	global_store_dwordx2 v[8:9], v[20:21], off offset:1536
	v_addc_co_u32_e32 v225, vcc, 0, v37, vcc
	v_cmp_lt_i32_e32 vcc, s4, v80
	s_or_b64 s[2:3], vcc, s[2:3]
	v_pk_add_f32 v[232:233], v[232:233], 1.0 op_sel_hi:[1,0]
	s_nop 0
	v_pk_fma_f32 v[16:17], v[232:233], v[16:17], v[228:229]
	v_pk_add_f32 v[228:229], v[234:235], 1.0 op_sel_hi:[1,0]
	v_cvt_pk_bf16_f32 v16, v16, v17
	v_pk_fma_f32 v[18:19], v[228:229], v[18:19], v[230:231]
	s_nop 0
	v_cvt_pk_bf16_f32 v17, v18, v19
	global_store_dwordx2 v[8:9], v[16:17], off offset:2048
	s_nop 0
	v_pk_add_f32 v[240:241], v[240:241], 1.0 op_sel_hi:[1,0]
	s_nop 0
	v_pk_fma_f32 v[12:13], v[240:241], v[12:13], v[236:237]
	v_pk_add_f32 v[236:237], v[242:243], 1.0 op_sel_hi:[1,0]
	v_cvt_pk_bf16_f32 v12, v12, v13
	v_pk_fma_f32 v[14:15], v[236:237], v[14:15], v[238:239]
	s_nop 0
	v_cvt_pk_bf16_f32 v13, v14, v15
	global_store_dwordx2 v[8:9], v[12:13], off offset:2560
	s_nop 0
	v_pk_add_f32 v[248:249], v[248:249], 1.0 op_sel_hi:[1,0]
	s_nop 0
	v_pk_fma_f32 v[4:5], v[248:249], v[4:5], v[244:245]
	v_pk_add_f32 v[244:245], v[250:251], 1.0 op_sel_hi:[1,0]
	v_cvt_pk_bf16_f32 v4, v4, v5
	v_pk_fma_f32 v[6:7], v[244:245], v[6:7], v[246:247]
	s_nop 0
	v_cvt_pk_bf16_f32 v5, v6, v7
	global_store_dwordx2 v[8:9], v[4:5], off offset:3072
	s_nop 0
	v_pk_add_f32 v[198:199], v[198:199], 1.0 op_sel_hi:[1,0]
	s_nop 0
	v_pk_fma_f32 v[0:1], v[198:199], v[0:1], v[210:211]
	v_pk_add_f32 v[210:211], v[200:201], 1.0 op_sel_hi:[1,0]
	v_cvt_pk_bf16_f32 v0, v0, v1
	v_pk_fma_f32 v[2:3], v[210:211], v[2:3], v[212:213]
	s_nop 0
	v_cvt_pk_bf16_f32 v1, v2, v3
	global_store_dwordx2 v[8:9], v[0:1], off offset:3584
	s_andn2_b64 exec, exec, s[2:3]
	s_cbranch_execnz .LBB0_2215
